# inproj K-loop converted to direct global-to-LDS loads; MLA loop K/V tile pointers strength-reduced to running SGPR pointers
# speedup vs baseline: 1.0248x; 1.0051x over previous
; DI int otid() { int t = threadIdx.x; asm volatile("" : "+v"(t)); return t; }
; DI u16* wl(const P& p, int l) { return (u16*)(p.ws + OFF_W) + (size_t)l * W_LAYER; }
; template <bool SW, class AL, class BL>
; DI void gemm_run16(int tid, char* lds, const AL& al, const BL& bl, int nk, f32x4 (&acc)[4][4], u32x4 (&ra0)[4], u32x4 (&rb0)[2], u32x4 (&ra1)[4], u32x4 (&rb1)[2]) {
;     ...
;   char* const wa = lds + lr * RB_ + ((lc ^ ((lr >> 1) & 7)) << 4);
;   const int o0 = (g ^ ((lane >> 1) & 7)) << 4, o1 = o0 ^ 64;
;   const int aoff = (wm * 64 + l15) * RB_, boff = AB + (wn * 64 + l15) * RB_;
; static __device__ __forceinline__ void phase_inproj(const P& p, int l, char* lds) {
;   const int tid = otid(), lane = tid & 63, wid = tid >> 6, r32 = lane & 31, hi = lane >> 5, wm = wid >> 1, wn = wid & 1, lr = tid >> 3;
;   const u16* H = (const u16*)(p.ws + OFF_H); const u16* W = wl(p, l) + W_IN;
;   u16* proj = (u16*)(p.ws + OFF_PROJ);
;   const float* cosS = (const float*)(p.ws + OFF_ROPE + ROPE_COSS); const float* sinS = (const float*)(p.ws + OFF_ROPE + ROPE_SINS);
;   const int ns = tile_steps(264, 12, 16, 2);
;   u32x4 ra0[4], rb0[2], ra1[4], rb1[2];
;   LdRows al, bl; int mt, nt;
;   auto mk = [&](int mt_, int nt_, LdRows& a_, LdRows& b_) {
; #pragma unroll
;     for (int j = 0; j < 4; ++j) a_.p[j] = H + (size_t)(mt_ * 256 + lr + 64 * j) * 1024;
; #pragma unroll
;     for (int j = 0; j < 2; ++j) b_.p[j] = W + (size_t)(nt_ * 128 + lr + 64 * j) * 1024;
;     b_.p[2] = b_.p[3] = b_.p[0];
;   };
;   int s = tile_next(0, ns, 264, 12, 16, 2, mt, nt);
;   if (s >= 0) { mk(mt, nt, al, bl); gemm_issue<4, 2>(tid, al, bl, 16, ra0, rb0, ra1, rb1); }
.LBB0_285:
	v_writelane_b32 v254, s42, 60
	s_andn2_b64 vcc, exec, s[0:1]
	v_ashrrev_i32_e32 v201, 1, v197
	v_lshrrev_b32_e32 v200, 2, v197
	v_writelane_b32 v254, s43, 61
	s_cbranch_vccnz .LBB0_339
	s_movk_i32 s0, 0x70
	s_waitcnt vmcnt(7)
	v_and_b32_e32 v50, 0xffffff80, v0
	v_bitop3_b32 v0, v0, s0, v197 bitop3:0x48
	v_add3_u32 v203, 0, v50, v0
	v_and_b32_e32 v251, 0x70, v203
	v_lshlrev_b32_e32 v0, 3, v197
	v_and_b32_e32 v50, 48, v197
	v_bitop3_b32 v204, v0, v50, s0 bitop3:0x6c
	v_lshlrev_b32_e32 v50, 7, v197
	v_and_b32_e32 v202, 15, v197
	v_and_b32_e32 v205, 0xffffffc0, v201
	v_and_b32_e32 v50, 0x2780, v50
	v_xor_b32_e32 v206, 64, v204
	v_readlane_b32 s0, v254, 28
	v_or_b32_e32 v0, v205, v202
	v_or_b32_e32 v51, 0x8000, v50
	v_add_u32_e32 v207, 0, v50
	v_add_u32_e32 v52, s0, v204
	v_add_u32_e32 v53, s0, v206
	v_and_b32_e32 v50, 12, v200
	v_readlane_b32 s0, v253, 41
	v_lshl_add_u32 v208, v0, 7, 0
	v_lshlrev_b32_e32 v0, 2, v50
	v_readlane_b32 s1, v253, 42
	s_lshl_b32 s84, s53, 6
	v_add_u32_e32 v209, 0x10900, v203
	v_lshl_add_u64 v[176:177], s[0:1], 0, v[0:1]
	v_readlane_b32 s0, v253, 43
	v_readlane_b32 s1, v253, 44
	v_add_u32_e32 v210, 0x12900, v203
	v_add_u32_e32 v211, 0x14900, v203
	v_lshl_add_u64 v[178:179], s[0:1], 0, v[0:1]
	v_readlane_b32 s0, v253, 46
	v_lshlrev_b32_e32 v0, 1, v50
	v_readlane_b32 s1, v253, 47
	v_add_u32_e32 v212, 0x16900, v203
	v_mov_b32_e32 v163, v1
	v_and_b32_e32 v213, 64, v197
	v_lshl_add_u64 v[180:181], s[30:31], 0, v[0:1]
	v_lshl_add_u64 v[182:183], s[64:65], 0, v[0:1]
	v_lshl_add_u64 v[184:185], s[0:1], 0, v[0:1]
	v_add_u32_e32 v214, v52, v51
	v_add_u32_e32 v215, v53, v51
	s_lshl_b64 s[12:13], s[84:85], 2
	v_lshlrev_b32_e32 v216, 2, v50
	s_branch .LBB0_288

; #define GLOAD(RA, RB, KT) do { const int kc_ = (KT) * 8 + lc; _Pragma("unroll") for (int j = 0; j < NA; ++j) RA[j] = al.load(j, kc_); _Pragma("unroll") for (int j = 0; j < NB; ++j) RB[j] = bl.load(j, kc_); } while (0)
; #define LWRITE(RA, RB, BUF) do { char* w_ = wa + (BUF) * STAGE; _Pragma("unroll") for (int j = 0; j < NA; ++j) *(u32x4*)(w_ + j * 64 * PITCH) = RA[j]; _Pragma("unroll") for (int j = 0; j < NB; ++j) *(u32x4*)(w_ + AB + j * 64 * PITCH) = RB[j]; } while (0)
; #define GLOAD(RA, RB, KT) do { const int kc_ = (KT) * 8 + lc; _Pragma("unroll") for (int j = 0; j < NA; ++j) RA[j] = al.load(j, kc_); _Pragma("unroll") for (int j = 0; j < NB; ++j) RB[j] = bl.load(j, kc_); } while (0)
; #define LWRITE(RA, RB, BUF) do { char* w_ = wa + (BUF) * STAGE; _Pragma("unroll") for (int j = 0; j < NA; ++j) *(u32x4*)(w_ + j * 64 * RB_) = RA[j]; _Pragma("unroll") for (int j = 0; j < NB; ++j) *(u32x4*)(w_ + AB + j * 64 * RB_) = RB[j]; } while (0)
; #define COMPUTE(BUF, RA, RB, WBUF) do { const char* sb = lds + (BUF) * STAGE; char* w_ = wa + (WBUF) * STAGE; \
;     KSTEP(o0); *(u32x4*)(w_) = RA[0]; *(u32x4*)(w_ + 64 * RB_) = RA[1]; *(u32x4*)(w_ + 128 * RB_) = RA[2]; \
;     KSTEP(o1); *(u32x4*)(w_ + 192 * RB_) = RA[3]; *(u32x4*)(w_ + AB) = RB[0]; *(u32x4*)(w_ + AB + 64 * RB_) = RB[1]; } while (0)
; template <bool SW, class AL, class BL>
; DI void gemm_run16(int tid, char* lds, const AL& al, const BL& bl, int nk, f32x4 (&acc)[4][4], u32x4 (&ra0)[4], u32x4 (&rb0)[2], u32x4 (&ra1)[4], u32x4 (&rb1)[2]) {
;     ...
;   const int kl = nk - 1;
;   LWRITE(ra0, rb0, 0);
;   __syncthreads();
; #pragma unroll 1
;   for (int kt = 0; kt < nk; kt += 2) {
;     GLOAD(ra0, rb0, (kt + 2 < kl ? kt + 2 : kl));
;     COMPUTE(0, ra1, rb1, 1);
;     __syncthreads();
;     if (kt + 1 >= nk) break;
;     GLOAD(ra1, rb1, (kt + 3 < kl ? kt + 3 : kl));
;     COMPUTE(1, ra0, rb0, 0);
;     __syncthreads();
; static __device__ __forceinline__ void phase_inproj(const P& p, int l, char* lds) {
;     ...
;     for (int a_ = 0; a_ < 4; ++a_)
; #pragma unroll
;       for (int b_ = 0; b_ < 4; ++b_) acc[a_][b_] = f32x4{0.f, 0.f, 0.f, 0.f};
;     __syncthreads();
;     gemm_run16<false>(tid, lds + LDS_SCR, al, bl, 16, acc, ra0, rb0, ra1, rb1);
.LBB0_288:
	v_mov_b32_e32 v50, 0
	s_mov_b32 s18, s22
	s_mov_b32 s19, s23
	s_mov_b32 s0, -2
	v_mov_b32_e32 v51, v50
	v_mov_b32_e32 v52, v50
	v_mov_b32_e32 v53, v50
	v_mov_b32_e32 v54, v50
	v_mov_b32_e32 v55, v50
	v_mov_b32_e32 v56, v50
	v_mov_b32_e32 v57, v50
	s_waitcnt vmcnt(4)
	v_mov_b32_e32 v58, v50
	v_mov_b32_e32 v59, v50
	v_mov_b32_e32 v60, v50
	v_mov_b32_e32 v61, v50
	v_mov_b32_e32 v70, v50
	v_mov_b32_e32 v71, v50
	v_mov_b32_e32 v72, v50
	v_mov_b32_e32 v73, v50
	v_mov_b32_e32 v78, v50
	v_mov_b32_e32 v79, v50
	v_mov_b32_e32 v80, v50
	v_mov_b32_e32 v81, v50
	v_mov_b32_e32 v94, v50
	v_mov_b32_e32 v95, v50
	v_mov_b32_e32 v96, v50
	v_mov_b32_e32 v97, v50
	v_mov_b32_e32 v102, v50
	v_mov_b32_e32 v103, v50
	v_mov_b32_e32 v104, v50
	v_mov_b32_e32 v105, v50
	v_mov_b32_e32 v106, v50
	v_mov_b32_e32 v107, v50
	v_mov_b32_e32 v108, v50
	v_mov_b32_e32 v109, v50
	v_mov_b32_e32 v66, v50
	v_mov_b32_e32 v67, v50
	v_mov_b32_e32 v68, v50
	v_mov_b32_e32 v69, v50
	v_mov_b32_e32 v62, v50
	v_mov_b32_e32 v63, v50
	v_mov_b32_e32 v64, v50
	v_mov_b32_e32 v65, v50
	v_mov_b32_e32 v74, v50
	v_mov_b32_e32 v75, v50
	v_mov_b32_e32 v76, v50
	v_mov_b32_e32 v77, v50
	v_mov_b32_e32 v82, v50
	v_mov_b32_e32 v83, v50
	v_mov_b32_e32 v84, v50
	v_mov_b32_e32 v85, v50
	v_mov_b32_e32 v90, v50
	v_mov_b32_e32 v91, v50
	v_mov_b32_e32 v92, v50
	v_mov_b32_e32 v93, v50
	v_mov_b32_e32 v86, v50
	v_mov_b32_e32 v87, v50
	v_mov_b32_e32 v88, v50
	v_mov_b32_e32 v89, v50
	v_mov_b32_e32 v98, v50
	v_mov_b32_e32 v99, v50
	v_mov_b32_e32 v100, v50
	v_mov_b32_e32 v101, v50
	v_mov_b32_e32 v110, v50
	v_mov_b32_e32 v111, v50
	v_mov_b32_e32 v112, v50
	v_mov_b32_e32 v113, v50
	s_barrier
	ds_write_b128 v203, v[26:29] offset:2304
	ds_write_b128 v203, v[30:33] offset:10496
	ds_write_b128 v203, v[34:37] offset:18688
	ds_write_b128 v203, v[42:45] offset:26880
	s_waitcnt vmcnt(3)
	ds_write_b128 v203, v[38:41] offset:35072
	s_waitcnt vmcnt(1)
	ds_write_b128 v203, v[46:49] offset:43264
	s_waitcnt vmcnt(0)
	ds_write_b128 v203, v[14:17] offset:51456
	ds_write_b128 v203, v[18:21] offset:59648
	ds_write_b128 v209, v[22:25]
	ds_write_b128 v210, v[6:9]
	ds_write_b128 v211, v[2:5]
	ds_write_b128 v212, v[10:13]
	s_waitcnt lgkmcnt(0)
	s_barrier
.LBB0_289:
	v_add_u32_e32 v0, v207, v204
	v_add_u32_e32 v122, v208, v204
	ds_read_b128 v[26:29], v0 offset:35072
	ds_read_b128 v[30:33], v0 offset:37120
	ds_read_b128 v[34:37], v122 offset:2304
	ds_read_b128 v[38:41], v122 offset:4352
	ds_read_b128 v[46:49], v0 offset:39168
	v_add_u32_e32 v130, v208, v206
	s_waitcnt lgkmcnt(2)
	v_mfma_f32_16x16x32_bf16 v[42:45], v[26:29], v[34:37], v[106:109]
	s_add_i32 s1, s0, 4
	s_min_u32 s1, s1, 15
	s_nop 0
	ds_read_b128 v[106:109], v0 offset:41216
	v_mfma_f32_16x16x32_bf16 v[102:105], v[30:33], v[34:37], v[102:105]
	v_add_u32_e32 v0, v207, v206
	s_waitcnt lgkmcnt(1)
	v_mfma_f32_16x16x32_bf16 v[94:97], v[46:49], v[34:37], v[94:97]
	s_waitcnt lgkmcnt(0)
	v_mfma_f32_16x16x32_bf16 v[34:37], v[106:109], v[34:37], v[78:81]
	v_mfma_f32_16x16x32_bf16 v[70:73], v[26:29], v[38:41], v[70:73]
	v_mfma_f32_16x16x32_bf16 v[58:61], v[30:33], v[38:41], v[58:61]
	v_mfma_f32_16x16x32_bf16 v[54:57], v[46:49], v[38:41], v[54:57]
	v_mfma_f32_16x16x32_bf16 v[38:41], v[106:109], v[38:41], v[50:53]
	s_nop 2
	ds_read_b128 v[50:53], v122 offset:6400
	ds_read_b128 v[78:81], v122 offset:8448
	ds_read_b128 v[18:21], v0 offset:35072
	ds_read_b128 v[22:25], v0 offset:37120
	s_waitcnt lgkmcnt(3)
	v_mfma_f32_16x16x32_bf16 v[66:69], v[26:29], v[50:53], v[66:69]
	v_mfma_f32_16x16x32_bf16 v[62:65], v[30:33], v[50:53], v[62:65]
	v_mfma_f32_16x16x32_bf16 v[74:77], v[46:49], v[50:53], v[74:77]
	v_mfma_f32_16x16x32_bf16 v[50:53], v[106:109], v[50:53], v[82:85]
	s_waitcnt lgkmcnt(2)
	v_mfma_f32_16x16x32_bf16 v[82:85], v[26:29], v[78:81], v[90:93]
	v_mfma_f32_16x16x32_bf16 v[86:89], v[30:33], v[78:81], v[86:89]
	ds_read_b128 v[26:29], v130 offset:2304
	ds_read_b128 v[30:33], v130 offset:4352
	ds_read_b128 v[118:121], v130 offset:8448
	v_mfma_f32_16x16x32_bf16 v[14:17], v[46:49], v[78:81], v[98:101]
	v_mfma_f32_16x16x32_bf16 v[78:81], v[106:109], v[78:81], v[110:113]
	s_nop 1
	ds_read_b128 v[98:101], v0 offset:39168
	ds_read_b128 v[106:109], v0 offset:41216
	v_lshl_or_b32 v0, s1, 7, v251
	s_waitcnt lgkmcnt(4)
	v_mfma_f32_16x16x32_bf16 v[90:93], v[18:21], v[26:29], v[42:45]
	v_lshl_add_u64 v[46:47], v[174:175], 0, v[0:1]
	s_add_i32 s1, s0, 2
	s_min_u32 s0, s1, 12
	v_mfma_f32_16x16x32_bf16 v[102:105], v[22:25], v[26:29], v[102:105]
	s_cmp_lt_u32 s1, 14
	s_waitcnt lgkmcnt(1)
	v_mfma_f32_16x16x32_bf16 v[94:97], v[98:101], v[26:29], v[94:97]
	s_waitcnt lgkmcnt(0)
	v_mfma_f32_16x16x32_bf16 v[110:113], v[106:109], v[26:29], v[34:37]
	ds_read_b128 v[26:29], v130 offset:6400
	v_lshl_add_u64 v[34:35], v[168:169], 0, v[0:1]
	v_mfma_f32_16x16x32_bf16 v[70:73], v[18:21], v[30:33], v[70:73]
	v_mfma_f32_16x16x32_bf16 v[58:61], v[22:25], v[30:33], v[58:61]
	v_mfma_f32_16x16x32_bf16 v[54:57], v[98:101], v[30:33], v[54:57]
	v_mfma_f32_16x16x32_bf16 v[114:117], v[106:109], v[30:33], v[38:41]
	v_lshl_add_u64 v[30:31], v[164:165], 0, v[0:1]
	v_lshl_add_u64 v[32:33], v[166:167], 0, v[0:1]
	s_waitcnt lgkmcnt(0)
	v_mfma_f32_16x16x32_bf16 v[66:69], v[18:21], v[26:29], v[66:69]
	v_lshl_add_u64 v[38:39], v[170:171], 0, v[0:1]
	v_lshl_add_u64 v[40:41], v[172:173], 0, v[0:1]
	v_lshl_or_b32 v0, s0, 7, v251
	v_mfma_f32_16x16x32_bf16 v[2:5], v[22:25], v[26:29], v[62:65]
	s_mov_b32 s0, s1
	v_mfma_f32_16x16x32_bf16 v[6:9], v[98:101], v[26:29], v[74:77]
	v_mfma_f32_16x16x32_bf16 v[10:13], v[106:109], v[26:29], v[50:53]
	s_waitcnt vmcnt(0) lgkmcnt(0)
	s_barrier
	s_cmp_lt_u32 s1, 14
	s_cbranch_scc0 .Linp_skip1
	s_mov_b32 m0, s98
	s_nop 0
	global_load_lds_dwordx4 v[30:31], off
	s_add_u32 m0, s98, 0x2000
	s_nop 0
	global_load_lds_dwordx4 v[32:33], off
	s_add_u32 m0, s98, 0x4000
	s_nop 0
	global_load_lds_dwordx4 v[34:35], off
	s_add_u32 m0, s98, 0x6000
	s_nop 0
	global_load_lds_dwordx4 v[38:39], off
	s_add_u32 m0, s98, 0x8000
	s_nop 0
	global_load_lds_dwordx4 v[40:41], off
	s_add_u32 m0, s98, 0xa000
	s_nop 0
	global_load_lds_dwordx4 v[46:47], off
; #define GLOAD(RA, RB, KT) do { const int kc_ = (KT) * 8 + lc; _Pragma("unroll") for (int j = 0; j < NA; ++j) RA[j] = al.load(j, kc_); _Pragma("unroll") for (int j = 0; j < NB; ++j) RB[j] = bl.load(j, kc_); } while (0)
; #define GLOAD(RA, RB, KT) do { const int kc_ = (KT) * 8 + lc; _Pragma("unroll") for (int j = 0; j < NA; ++j) RA[j] = al.load(j, kc_); _Pragma("unroll") for (int j = 0; j < NB; ++j) RB[j] = bl.load(j, kc_); } while (0)
; #define COMPUTE(BUF, RA, RB, WBUF) do { const char* sb = lds + (BUF) * STAGE; char* w_ = wa + (WBUF) * STAGE; \
;     KSTEP(o0); *(u32x4*)(w_) = RA[0]; *(u32x4*)(w_ + 64 * RB_) = RA[1]; *(u32x4*)(w_ + 128 * RB_) = RA[2]; \
;     KSTEP(o1); *(u32x4*)(w_ + 192 * RB_) = RA[3]; *(u32x4*)(w_ + AB) = RB[0]; *(u32x4*)(w_ + AB + 64 * RB_) = RB[1]; } while (0)
; template <bool SW, class AL, class BL>
; DI void gemm_run16(int tid, char* lds, const AL& al, const BL& bl, int nk, f32x4 (&acc)[4][4], u32x4 (&ra0)[4], u32x4 (&rb0)[2], u32x4 (&ra1)[4], u32x4 (&rb1)[2]) {
;     ...
;   for (int kt = 0; kt < nk; kt += 2) {
;     GLOAD(ra0, rb0, (kt + 2 < kl ? kt + 2 : kl));
;     COMPUTE(0, ra1, rb1, 1);
;     __syncthreads();
;     if (kt + 1 >= nk) break;
;     GLOAD(ra1, rb1, (kt + 3 < kl ? kt + 3 : kl));
;     COMPUTE(1, ra0, rb0, 0);
;     __syncthreads();
.Linp_skip1:
	ds_read_b128 v[50:53], v214
	ds_read_b128 v[62:65], v214 offset:2048
	v_mfma_f32_16x16x32_bf16 v[18:21], v[18:21], v[118:121], v[82:85]
	v_mfma_f32_16x16x32_bf16 v[74:77], v[106:109], v[118:121], v[78:81]
	s_nop 2
	ds_read_b128 v[78:81], v122 offset:51456
	ds_read_b128 v[82:85], v122 offset:53504
	v_mfma_f32_16x16x32_bf16 v[22:25], v[22:25], v[118:121], v[86:89]
	v_mfma_f32_16x16x32_bf16 v[14:17], v[98:101], v[118:121], v[14:17]
	s_waitcnt lgkmcnt(1)
	v_mfma_f32_16x16x32_bf16 v[86:89], v[50:53], v[78:81], v[90:93]
	s_nop 2
	ds_read_b128 v[90:93], v214 offset:4096
	v_mfma_f32_16x16x32_bf16 v[98:101], v[62:65], v[78:81], v[102:105]
	s_nop 2
	ds_read_b128 v[102:105], v214 offset:6144
	s_waitcnt lgkmcnt(1)
	v_mfma_f32_16x16x32_bf16 v[94:97], v[90:93], v[78:81], v[94:97]
	s_waitcnt lgkmcnt(0)
	v_mfma_f32_16x16x32_bf16 v[78:81], v[102:105], v[78:81], v[110:113]
	ds_read_b128 v[106:109], v122 offset:55552
	s_nop 1
	ds_read_b128 v[110:113], v122 offset:57600
	v_mfma_f32_16x16x32_bf16 v[70:73], v[50:53], v[82:85], v[70:73]
	v_mfma_f32_16x16x32_bf16 v[58:61], v[62:65], v[82:85], v[58:61]
	v_mfma_f32_16x16x32_bf16 v[54:57], v[90:93], v[82:85], v[54:57]
	v_mfma_f32_16x16x32_bf16 v[82:85], v[102:105], v[82:85], v[114:117]
	s_waitcnt lgkmcnt(1)
	v_mfma_f32_16x16x32_bf16 v[66:69], v[50:53], v[106:109], v[66:69]
	v_mfma_f32_16x16x32_bf16 v[2:5], v[62:65], v[106:109], v[2:5]
	s_waitcnt lgkmcnt(0)
	v_mfma_f32_16x16x32_bf16 v[18:21], v[50:53], v[110:113], v[18:21]
	v_mfma_f32_16x16x32_bf16 v[22:25], v[62:65], v[110:113], v[22:25]
	v_mfma_f32_16x16x32_bf16 v[114:117], v[90:93], v[110:113], v[14:17]
	s_nop 2
	ds_read_b128 v[14:17], v215
	ds_read_b128 v[118:121], v215 offset:2048
	ds_read_b128 v[50:53], v130 offset:51456
	ds_read_b128 v[62:65], v130 offset:53504
	ds_read_b128 v[122:125], v215 offset:4096
	ds_read_b128 v[126:129], v215 offset:6144
	v_mfma_f32_16x16x32_bf16 v[6:9], v[90:93], v[106:109], v[6:9]
	v_mfma_f32_16x16x32_bf16 v[10:13], v[102:105], v[106:109], v[10:13]
	v_mfma_f32_16x16x32_bf16 v[110:113], v[102:105], v[110:113], v[74:77]
	s_waitcnt lgkmcnt(3)
	v_mfma_f32_16x16x32_bf16 v[106:109], v[14:17], v[50:53], v[86:89]
	v_mfma_f32_16x16x32_bf16 v[102:105], v[118:121], v[50:53], v[98:101]
	s_waitcnt lgkmcnt(1)
	v_mfma_f32_16x16x32_bf16 v[94:97], v[122:125], v[50:53], v[94:97]
	s_waitcnt lgkmcnt(0)
	v_mfma_f32_16x16x32_bf16 v[78:81], v[126:129], v[50:53], v[78:81]
	v_mfma_f32_16x16x32_bf16 v[50:53], v[126:129], v[62:65], v[82:85]
	s_nop 2
	ds_read_b128 v[82:85], v130 offset:55552
	ds_read_b128 v[130:133], v130 offset:57600
	v_mfma_f32_16x16x32_bf16 v[70:73], v[14:17], v[62:65], v[70:73]
	v_mfma_f32_16x16x32_bf16 v[58:61], v[118:121], v[62:65], v[58:61]
	v_mfma_f32_16x16x32_bf16 v[54:57], v[122:125], v[62:65], v[54:57]
	s_waitcnt lgkmcnt(1)
	v_mfma_f32_16x16x32_bf16 v[62:65], v[118:121], v[82:85], v[2:5]
	v_mfma_f32_16x16x32_bf16 v[74:77], v[122:125], v[82:85], v[6:9]
	s_nop 1
	v_lshl_add_u64 v[2:3], v[164:165], 0, v[0:1]
	v_lshl_add_u64 v[4:5], v[166:167], 0, v[0:1]
	v_lshl_add_u64 v[6:7], v[168:169], 0, v[0:1]
	v_lshl_add_u64 v[8:9], v[170:171], 0, v[0:1]
	v_mfma_f32_16x16x32_bf16 v[66:69], v[14:17], v[82:85], v[66:69]
	v_mfma_f32_16x16x32_bf16 v[82:85], v[126:129], v[82:85], v[10:13]
	s_nop 2
	v_lshl_add_u64 v[10:11], v[172:173], 0, v[0:1]
	s_waitcnt lgkmcnt(0)
	v_mfma_f32_16x16x32_bf16 v[90:93], v[14:17], v[130:133], v[18:21]
	v_lshl_add_u64 v[12:13], v[174:175], 0, v[0:1]
	s_nop 0
	v_mfma_f32_16x16x32_bf16 v[86:89], v[118:121], v[130:133], v[22:25]
	s_nop 2
	s_nop 0
	s_nop 0
	s_nop 0
	v_mfma_f32_16x16x32_bf16 v[98:101], v[122:125], v[130:133], v[114:117]
	s_waitcnt vmcnt(0) lgkmcnt(0)
	s_barrier
	s_cmp_lt_u32 s1, 14
	s_cbranch_scc0 .Linp_skip2
	s_add_u32 m0, s98, 0xbe80
	s_nop 0
	global_load_lds_dwordx4 v[2:3], off offset:384
	s_add_u32 m0, s98, 0xde80
	s_nop 0
	global_load_lds_dwordx4 v[4:5], off offset:384
	s_add_u32 m0, s98, 0xfe80
	s_nop 0
	global_load_lds_dwordx4 v[6:7], off offset:384
	s_add_u32 m0, s98, 0x11e80
	s_nop 0
	global_load_lds_dwordx4 v[8:9], off offset:384
	s_add_u32 m0, s98, 0x13e80
	s_nop 0
	global_load_lds_dwordx4 v[10:11], off offset:384
	s_add_u32 m0, s98, 0x15e80
	s_nop 0
	global_load_lds_dwordx4 v[12:13], off offset:384
.Linp_skip2:
	v_mfma_f32_16x16x32_bf16 v[110:113], v[126:129], v[130:133], v[110:113]
	s_cmp_lt_u32 s1, 14
	s_cbranch_scc1 .LBB0_289
	s_add_i32 s8, s5, 1
	s_cmp_ge_i32 s8, s4
	s_cbranch_scc1 .LBB0_301
	s_lshl_b32 s0, s5, 3
	v_readlane_b32 s1, v254, 25
	s_add_i32 s17, s1, s0
	s_mul_i32 s0, s66, s8
	s_add_i32 s9, s94, s0
	s_mov_b32 s22, 0
	s_mov_b32 s23, 0
	s_branch .LBB0_293

; template <int DQK>
; DI void attn_unit(int tid, char* lds, const u16* Qp, const u16* K1, const u16* V1, int nt1, int kpos0, const u16* K2, const u16* V2, int nt2, int qpos0, bool mask, float m_init, float l_init, u16* Op) {
;     ...
;   f32x16 o0, o1;
; #pragma unroll
;   for (int r = 0; r < 16; ++r) { o0[r] = 0.f; o1[r] = 0.f; }
;   constexpr float THR = 8.f;
;   float mrun = m_init, lrun = hi == 0 ? l_init : 0.f;
;   f32x16 negm;
; #pragma unroll
;   for (int r = 0; r < 16; ++r) negm[r] = -mrun;
;   const int NT = nt1 + nt2;
;   const int qpos = qpos0 + wid * 32 + r32;
;   u32x4 sk0, sk1, sv;
;   auto gl = [&](int i) {
;     const u16* kp; const u16* vp;
;     if (i < nt1) { kp = K1 + (size_t)i * 64 * DQK; vp = V1 + (size_t)i * 4096; } else { kp = K2 + (size_t)(i - nt1) * 64 * DQK; vp = V2 + (size_t)(i - nt1) * 4096; }
;     sk0 = *(const u32x4*)(kp + (size_t)tid * 8); sk1 = *(const u32x4*)(kp + (size_t)idl * 8); sv = *(const u32x4*)(vp + (size_t)tid * 8);
;   };
;     ...
;   gl(0); sw(0);
;   if (NT > 1) { gl(1); sw(1); }
;   __syncthreads();
;   f32x16 pA0, pA1, pB0, pB1;
; #pragma unroll
;   for (int r = 0; r < 16; ++r) { pB0[r] = 0.f; pB1[r] = 0.f; }
;   if (live(0)) qk(0, pA0, pA1);
;   int s_cur = 0, s_nxt = 1, s_wr = 2;
; #pragma unroll 1
;   for (int i = 0; i < NT; i += 2) {
;     step(pA0, pA1, pB0, pB1, i, s_cur, s_nxt, s_wr);
;     if (i + 1 >= NT) break;
;     step(pB0, pB1, pA0, pA1, i + 1, s_nxt, s_wr, s_cur);
;     const int t_ = s_cur; s_cur = s_wr; s_wr = s_nxt; s_nxt = t_;
;   }
.LBB0_679:
	s_or_b64 exec, exec, s[0:1]
	s_waitcnt vmcnt(0)
	ds_write_b128 v0, v[194:197] offset:35072
	s_waitcnt lgkmcnt(0)
	s_barrier
	ds_read_b128 v[2:5], v247 offset:256
	ds_read_b128 v[6:9], v247 offset:288
	v_readlane_b32 s16, v254, 29
	v_readlane_b32 s30, v254, 43
	v_readlane_b32 s31, v254, 44
	v_readlane_b32 s17, v254, 30
	v_readlane_b32 s18, v254, 31
	v_readlane_b32 s19, v254, 32
	v_readlane_b32 s20, v254, 33
	v_readlane_b32 s21, v254, 34
	v_readlane_b32 s22, v254, 35
	v_readlane_b32 s23, v254, 36
	v_readlane_b32 s24, v254, 37
	v_readlane_b32 s25, v254, 38
	v_readlane_b32 s26, v254, 39
	v_readlane_b32 s27, v254, 40
	v_readlane_b32 s28, v254, 41
	v_readlane_b32 s29, v254, 42
	s_mov_b32 s30, s16
	s_mov_b32 s31, s16
	s_mov_b32 s17, s16
	s_mov_b32 s18, s16
	s_mov_b32 s19, s16
	s_mov_b32 s20, s16
	s_mov_b32 s21, s16
	s_mov_b32 s22, s16
	s_mov_b32 s23, s16
	s_mov_b32 s24, s16
	s_mov_b32 s25, s16
	s_mov_b32 s26, s16
	s_mov_b32 s27, s16
	s_mov_b32 s28, s16
	s_mov_b32 s29, s16
	v_mov_b64_e32 v[80:81], s[30:31]
	v_mov_b64_e32 v[78:79], s[28:29]
	v_mov_b64_e32 v[76:77], s[26:27]
	v_mov_b64_e32 v[74:75], s[24:25]
	v_mov_b64_e32 v[72:73], s[22:23]
	v_mov_b64_e32 v[70:71], s[20:21]
	v_mov_b64_e32 v[68:69], s[18:19]
	v_mov_b64_e32 v[66:67], s[16:17]
	s_mov_b32 s0, s16
	v_writelane_b32 v254, s0, 29
	s_waitcnt lgkmcnt(1)
	v_mfma_f32_32x32x16_bf16 v[50:65], v[2:5], v[162:165], v[66:81]
	ds_read_b128 v[2:5], v247 offset:6912
	ds_read_b128 v[10:13], v247 offset:6944
	v_writelane_b32 v254, s1, 30
	v_writelane_b32 v254, s2, 31
	v_writelane_b32 v254, s3, 32
	v_writelane_b32 v254, s4, 33
	v_writelane_b32 v254, s5, 34
	v_writelane_b32 v254, s6, 35
	s_waitcnt lgkmcnt(1)
	v_mfma_f32_32x32x16_bf16 v[66:81], v[2:5], v[162:165], v[66:81]
	ds_read_b128 v[2:5], v247 offset:320
	v_writelane_b32 v254, s7, 36
	v_writelane_b32 v254, s8, 37
	v_writelane_b32 v254, s9, 38
	v_writelane_b32 v254, s10, 39
	v_writelane_b32 v254, s11, 40
	v_writelane_b32 v254, s12, 41
	v_mfma_f32_32x32x16_bf16 v[50:65], v[6:9], v[166:169], v[50:65]
	v_writelane_b32 v254, s13, 42
	v_writelane_b32 v254, s14, 43
	v_writelane_b32 v254, s15, 44
	s_lshl_b64 s[0:1], s[82:83], 8
	s_add_u32 s0, s0, 0x60000
	s_addc_u32 s1, s1, 0
	s_mul_i32 s4, s1, 0xc0
	s_waitcnt lgkmcnt(1)
	v_mfma_f32_32x32x16_bf16 v[66:81], v[10:13], v[166:169], v[66:81]
	ds_read_b128 v[6:9], v247 offset:6976
	ds_read_b128 v[10:13], v247 offset:352
	ds_read_b128 v[14:17], v247 offset:7008
	ds_read_b128 v[36:39], v247 offset:7040
	ds_read_b128 v[82:85], v247 offset:7072
	ds_read_b128 v[18:21], v247 offset:384
	ds_read_b128 v[42:45], v247 offset:416
	s_mul_hi_u32 s5, s0, 0xc0
	s_add_i32 s5, s5, s4
	s_mul_i32 s4, s0, 0xc0
	v_readlane_b32 s14, v253, 58
	s_waitcnt lgkmcnt(7)
	v_mfma_f32_32x32x16_bf16 v[50:65], v[2:5], v[170:173], v[50:65]
	v_readlane_b32 s15, v253, 59
	s_add_u32 s4, s14, s4
	s_addc_u32 s5, s15, s5
	s_lshl_b64 s[0:1], s[0:1], 7
	v_readlane_b32 s14, v253, 60
	v_mov_b32_e32 v0, v1
	v_mov_b32_e32 v2, v1
	s_waitcnt lgkmcnt(6)
	v_mfma_f32_32x32x16_bf16 v[66:81], v[6:9], v[170:173], v[66:81]
	v_mov_b32_e32 v3, v1
	v_mov_b32_e32 v4, v1
	v_mov_b32_e32 v5, v1
	v_mov_b32_e32 v6, v1
	v_mov_b32_e32 v7, v1
	v_mov_b32_e32 v8, v1
	v_mov_b32_e32 v9, v1
	s_waitcnt lgkmcnt(5)
	v_mfma_f32_32x32x16_bf16 v[50:65], v[10:13], v[174:177], v[50:65]
	v_mov_b32_e32 v10, v1
	v_mov_b32_e32 v11, v1
	v_mov_b32_e32 v12, v1
	v_mov_b32_e32 v13, v1
	v_readlane_b32 s15, v253, 61
	s_add_u32 s18, s14, s0
	v_bfrev_b32_e32 v34, 1
	s_waitcnt lgkmcnt(4)
	v_mfma_f32_32x32x16_bf16 v[66:81], v[14:17], v[174:177], v[66:81]
	v_mov_b32_e32 v14, v1
	v_mov_b32_e32 v15, v1
	s_addc_u32 s19, s15, s1
	s_mov_b32 s20, 0
	v_mov_b32_e32 v216, 0
	s_mov_b32 s21, 1
	s_mov_b32 s0, 2
	s_waitcnt lgkmcnt(1)
	v_mfma_f32_32x32x16_bf16 v[50:65], v[18:21], v[178:181], v[50:65]
	v_mov_b64_e32 v[32:33], v[14:15]
	v_mov_b64_e32 v[30:31], v[12:13]
	v_mov_b64_e32 v[28:29], v[10:11]
	v_mov_b64_e32 v[26:27], v[8:9]
	v_mov_b64_e32 v[24:25], v[6:7]
	v_mov_b64_e32 v[22:23], v[4:5]
	v_mov_b64_e32 v[20:21], v[2:3]
	v_mfma_f32_32x32x16_bf16 v[66:81], v[36:39], v[178:181], v[66:81]
	v_mov_b64_e32 v[18:19], v[0:1]
	v_mov_b64_e32 v[16:17], v[14:15]
	s_mov_b32 s22, 3
	v_mov_b32_e32 v215, 0
	v_mov_b64_e32 v[14:15], v[12:13]
	v_mov_b64_e32 v[12:13], v[10:11]
	v_mov_b64_e32 v[10:11], v[8:9]
	s_waitcnt lgkmcnt(0)
	v_mfma_f32_32x32x16_bf16 v[50:65], v[42:45], v[182:185], v[50:65]
	v_mov_b64_e32 v[8:9], v[6:7]
	v_mov_b64_e32 v[6:7], v[4:5]
	v_mov_b64_e32 v[4:5], v[2:3]
	v_mov_b64_e32 v[2:3], v[0:1]
	v_mov_b32_e32 v35, v34
	v_mov_b32_e32 v36, v34
	v_mov_b32_e32 v37, v34
	v_mfma_f32_32x32x16_bf16 v[66:81], v[82:85], v[182:185], v[66:81]
	v_mov_b32_e32 v38, v34
	v_mov_b32_e32 v39, v34
	v_mov_b32_e32 v40, v34
	v_mov_b32_e32 v41, v34
	v_mov_b32_e32 v42, v34
	v_mov_b32_e32 v43, v34
	v_mov_b32_e32 v44, v34
	v_mov_b32_e32 v45, v34
	v_mov_b32_e32 v46, v34
	v_mov_b32_e32 v47, v34
	v_mov_b32_e32 v48, v34
	v_mov_b32_e32 v49, v34
	s_add_u32 s30, s10, 0x6000
	s_addc_u32 s31, s11, 0
	s_add_u32 s34, s12, 0x4000
	s_addc_u32 s35, s13, 0
.LBB0_680:
	s_add_i32 s24, s22, -3
	s_cmpk_lt_u32 s24, 0x82
	s_mov_b32 s23, s0
	s_cselect_b64 s[16:17], -1, 0
	s_cmpk_gt_u32 s24, 0x81
	s_cbranch_scc1 .LBB0_682
	v_lshl_add_u64 v[82:83], s[30:31], 0, v[204:205]
	v_lshl_add_u64 v[84:85], s[30:31], 0, v[212:213]
	global_load_dwordx4 v[186:189], v[82:83], off
	global_load_dwordx4 v[190:193], v[84:85], off
	v_lshl_add_u64 v[82:83], s[34:35], 0, v[204:205]
	global_load_dwordx4 v[194:197], v[82:83], off
	s_add_u32 s30, s30, 0x3000
	s_addc_u32 s31, s31, 0
	s_add_u32 s34, s34, 0x2000
	s_addc_u32 s35, s35, 0

; template <int DQK>
; DI void attn_unit(int tid, char* lds, const u16* Qp, const u16* K1, const u16* V1, int nt1, int kpos0, const u16* K2, const u16* V2, int nt2, int qpos0, bool mask, float m_init, float l_init, u16* Op) {
;     ...
;   auto gl = [&](int i) {
;     const u16* kp; const u16* vp;
;     if (i < nt1) { kp = K1 + (size_t)i * 64 * DQK; vp = V1 + (size_t)i * 4096; } else { kp = K2 + (size_t)(i - nt1) * 64 * DQK; vp = V2 + (size_t)(i - nt1) * 4096; }
;     sk0 = *(const u32x4*)(kp + (size_t)tid * 8); sk1 = *(const u32x4*)(kp + (size_t)idl * 8); sv = *(const u32x4*)(vp + (size_t)tid * 8);
;   };
.LBB0_689:
	s_cmpk_lt_u32 s24, 0x81
	s_cselect_b64 s[16:17], -1, 0
	s_cmpk_gt_u32 s24, 0x80
	s_waitcnt lgkmcnt(0)
	s_barrier
	s_cbranch_scc1 .LBB0_691
	v_lshl_add_u64 v[50:51], s[30:31], 0, v[204:205]
	v_lshl_add_u64 v[52:53], s[30:31], 0, v[212:213]
	global_load_dwordx4 v[186:189], v[50:51], off
	global_load_dwordx4 v[190:193], v[52:53], off
	v_lshl_add_u64 v[50:51], s[34:35], 0, v[204:205]
	global_load_dwordx4 v[194:197], v[50:51], off
	s_add_u32 s30, s30, 0x3000
	s_addc_u32 s31, s31, 0
	s_add_u32 s34, s34, 0x2000
	s_addc_u32 s35, s35, 0
	s_cmpk_eq_u32 s24, 0x7c
	s_cselect_b32 s30, s4, s30
	s_cselect_b32 s31, s5, s31
	s_cselect_b32 s34, s18, s34
	s_cselect_b32 s35, s19, s35
